# v39 + P3 MODE 0 steady steps: first two PV MFMAs issued inside the row-max tree (tree reordered accumulator-by-accumulator, no s_nop 6)
# baseline (speedup 1.0000x reference)
.Lat0_c1:
	s_add_i32 s17, s30, -1
	v_bfe_u32 v80, v80, s17, 1
	v_add_u32_e32 v0, s16, v200
	v_cmp_eq_u32_e32 vcc, 1, v80
	s_nop 1
	v_cndmask_b32_e64 v80, v217, -v196, vcc
	v_cndmask_b32_e64 v81, v217, -v196, vcc
	v_mov_b64_e32 v[82:83], v[80:81]
	v_mov_b64_e32 v[84:85], v[80:81]
	v_mov_b64_e32 v[86:87], v[80:81]
	v_mov_b64_e32 v[88:89], v[80:81]
	v_mov_b64_e32 v[90:91], v[80:81]
	v_mov_b64_e32 v[92:93], v[80:81]
	v_mov_b64_e32 v[94:95], v[80:81]
	ds_read_b64_tr_b16 v[6:7], v0 offset:24576
	ds_read_b64_tr_b16 v[8:9], v0 offset:25088
	v_mfma_f32_32x32x16_bf16 v[96:111], v[172:175], v[136:139], v[80:95]
	v_add_f32_e32 v2, v64, v65
	v_add_f32_e32 v2, v66, v2
	v_add_f32_e32 v2, v67, v2
	v_add_f32_e32 v2, v68, v2
	v_add_f32_e32 v10, v69, v2
	v_cvt_pk_bf16_f32 v140, v64, v65
	v_cvt_pk_bf16_f32 v141, v66, v67
	ds_read_b64_tr_b16 v[2:3], v0 offset:28672
	ds_read_b64_tr_b16 v[4:5], v0 offset:29184
	v_mfma_f32_32x32x16_bf16 v[80:95], v[168:171], v[136:139], v[80:95]
	v_add_f32_e32 v10, v70, v10
	v_add_f32_e32 v10, v71, v10
	v_add_f32_e32 v10, v72, v10
	v_add_f32_e32 v14, v73, v10
	v_cvt_pk_bf16_f32 v142, v68, v69
	v_cvt_pk_bf16_f32 v143, v70, v71
	ds_read_b64_tr_b16 v[10:11], v0 offset:25600
	ds_read_b64_tr_b16 v[12:13], v0 offset:26112
	v_mfma_f32_32x32x16_bf16 v[96:111], v[164:167], v[128:131], v[96:111]
	v_add_f32_e32 v14, v74, v14
	v_add_f32_e32 v14, v75, v14
	v_add_f32_e32 v14, v76, v14
	v_add_f32_e32 v14, v77, v14
	v_cvt_pk_bf16_f32 v132, v72, v73
	v_cvt_pk_bf16_f32 v133, v74, v75
	ds_read_b64_tr_b16 v[64:65], v0 offset:29696
	ds_read_b64_tr_b16 v[66:67], v0 offset:30208
	v_mfma_f32_32x32x16_bf16 v[80:95], v[160:163], v[128:131], v[80:95]
	v_add_f32_e32 v14, v78, v14
	v_add_f32_e32 v14, v79, v14
	v_add_f32_e32 v14, v48, v14
	v_add_f32_e32 v14, v49, v14
	v_cvt_pk_bf16_f32 v134, v76, v77
	v_cvt_pk_bf16_f32 v135, v78, v79
	ds_read_b64_tr_b16 v[68:69], v0 offset:26624
	ds_read_b64_tr_b16 v[70:71], v0 offset:27136
	v_mfma_f32_32x32x16_bf16 v[96:111], v[156:159], v[116:119], v[96:111]
	v_add_f32_e32 v14, v50, v14
	v_add_f32_e32 v14, v51, v14
	v_add_f32_e32 v14, v52, v14
	v_add_f32_e32 v14, v53, v14
	v_cvt_pk_bf16_f32 v124, v48, v49
	v_cvt_pk_bf16_f32 v125, v50, v51
	ds_read_b64_tr_b16 v[72:73], v0 offset:30720
	ds_read_b64_tr_b16 v[74:75], v0 offset:31232
	v_mfma_f32_32x32x16_bf16 v[80:95], v[152:155], v[116:119], v[80:95]
	v_add_f32_e32 v14, v54, v14
	v_add_f32_e32 v14, v55, v14
	v_add_f32_e32 v14, v56, v14
	v_add_f32_e32 v14, v57, v14
	v_cvt_pk_bf16_f32 v126, v52, v53
	v_cvt_pk_bf16_f32 v127, v54, v55
	ds_read_b64_tr_b16 v[76:77], v0 offset:27648
	ds_read_b64_tr_b16 v[78:79], v0 offset:28160
	v_mfma_f32_32x32x16_bf16 v[96:111], v[148:151], v[112:115], v[96:111]
	v_add_f32_e32 v14, v58, v14
	v_add_f32_e32 v14, v59, v14
	v_add_f32_e32 v14, v60, v14
	v_add_f32_e32 v14, v61, v14
	v_cvt_pk_bf16_f32 v120, v56, v57
	v_cvt_pk_bf16_f32 v121, v58, v59
	ds_read_b64_tr_b16 v[148:149], v0 offset:31744
	ds_read_b64_tr_b16 v[150:151], v0 offset:32256
	v_mfma_f32_32x32x16_bf16 v[80:95], v[144:147], v[112:115], v[80:95]
	v_add_f32_e32 v0, v62, v14
	v_add_f32_e32 v0, v63, v0
	v_cvt_pk_bf16_f32 v122, v60, v61
	v_cvt_pk_bf16_f32 v123, v62, v63
	v_max_f32_e32 v48, v96, v97
	v_max3_f32 v49, v98, v99, v100
	v_max3_f32 v48, v48, v101, v102
	v_max3_f32 v49, v49, v103, v104
	s_waitcnt lgkmcnt(14)
	v_mfma_f32_32x32x16_bf16 v[32:47], v[140:143], v[6:9], v[32:47]
	v_max3_f32 v48, v48, v105, v106
	v_max3_f32 v49, v49, v107, v108
	v_max3_f32 v48, v48, v109, v110
	v_max3_f32 v49, v49, v111, v48
	v_add_f32_e32 v14, v202, v0
	v_max3_f32 v15, v80, v81, v82
	v_max3_f32 v50, v83, v84, v85
	v_max3_f32 v15, v15, v86, v87
	s_waitcnt lgkmcnt(12)
	v_mfma_f32_32x32x16_bf16 v[16:31], v[140:143], v[2:5], v[16:31]
	v_max3_f32 v50, v50, v88, v89
	v_max3_f32 v15, v15, v90, v91
	v_max3_f32 v50, v50, v92, v93
	v_max3_f32 v15, v15, v94, v95
	v_max3_f32 v0, v15, v50, v49
	v_mov_b32_e32 v15, v0
	s_nop 1
	v_permlane32_swap_b32_e32 v0, v15
	s_add_u32 s16, s14, 0xffff8000
	s_addc_u32 s17, s15, -1
	s_add_i32 s18, s29, s44
	s_mov_b32 s19, m0
	s_mov_b32 m0, s18
	s_nop 0
	global_load_lds_dwordx4 v197, s[16:17]
	s_mov_b32 m0, s19
	v_max_f32_e32 v0, v0, v15
	s_add_i32 s16, s34, s45
	s_mov_b32 s17, m0
	s_mov_b32 m0, s16
	s_nop 0
	global_load_lds_dwordx4 v198, s[12:13]
	s_mov_b32 m0, s17
	v_cmp_lt_f32_e32 vcc, s47, v0
	s_cmp_lg_u64 vcc, 0
	s_cselect_b64 s[16:17], -1, 0
	s_cbranch_vccnz .LBB0_1613
; #define WAIT_BAR(N) asm volatile("s_waitcnt vmcnt(" #N ") lgkmcnt(0)\n\ts_barrier":::"memory")
; #define RESC() do { if (resc) { asm volatile("s_waitcnt lgkmcnt(0)" ::: "memory"); \
;       _Pragma("unroll") for (int d_ = 0; d_ < 2; ++d_) _Pragma("unroll") for (int r = 0; r < 16; ++r) o[d_][r] *= wsf[crow(r, hi)]; } } while (0)
; #define ROT() do { sl_prev = sl_cur; sl_cur = sl_next; sl_next = (sl_next == (NSLOT - 1) * SLOTB) ? 0 : sl_next + SLOTB; } while (0)
; template <int MODE, int THRL>
; __device__ __forceinline__ void attn_unit(const Prm& P, int b, int h, int qb, LAS char* shm, int wid) {
;     ...
;   int t = 1;
;     ...
;   for (; t + 5 < NT; t += 2) {
;     STEP(pB0, pB1, pA0, pA1, t, true, true, true);     WAIT_BAR(2); RESC(); ROT();
;     STEP(pA0, pA1, pB0, pB1, t + 1, true, true, true); WAIT_BAR(2); RESC(); ROT();
.LBB0_1606:
	v_exp_f32_e32 v96, v96
	v_exp_f32_e32 v97, v97
	v_exp_f32_e32 v98, v98
	v_exp_f32_e32 v99, v99
	v_exp_f32_e32 v100, v100
	v_exp_f32_e32 v101, v101
	v_exp_f32_e32 v102, v102
	v_exp_f32_e32 v103, v103
	v_add_u32_e32 v0, s34, v199
	ds_read_b128 v[6:9], v0
	ds_read_b128 v[172:175], v0 offset:512
	s_waitcnt lgkmcnt(12)
	v_mfma_f32_32x32x16_bf16 v[32:47], v[132:135], v[10:13], v[32:47]
	v_exp_f32_e32 v104, v104
	v_exp_f32_e32 v105, v105
	v_exp_f32_e32 v106, v106
	v_exp_f32_e32 v107, v107
	ds_read_b128 v[168:171], v0 offset:2048
	ds_read_b128 v[164:167], v0 offset:2560
	s_waitcnt lgkmcnt(12)
	v_mfma_f32_32x32x16_bf16 v[16:31], v[132:135], v[64:67], v[16:31]
	v_exp_f32_e32 v108, v108
	v_exp_f32_e32 v109, v109
	v_exp_f32_e32 v110, v110
	v_exp_f32_e32 v111, v111
	ds_read_b128 v[160:163], v0 offset:4096
	ds_read_b128 v[156:159], v0 offset:4608
	s_waitcnt lgkmcnt(12)
	v_mfma_f32_32x32x16_bf16 v[32:47], v[124:127], v[68:71], v[32:47]
	v_exp_f32_e32 v80, v80
	v_exp_f32_e32 v81, v81
	v_exp_f32_e32 v82, v82
	v_exp_f32_e32 v83, v83
	ds_read_b128 v[152:155], v0 offset:6144
	ds_read_b128 v[144:147], v0 offset:6656
	s_and_b32 s18, s30, 0x3fffffe0
	v_lshl_add_u32 v0, s18, 2, v194
	ds_read_b32 v48, v0 offset:49408
	s_waitcnt lgkmcnt(13)
	v_mfma_f32_32x32x16_bf16 v[16:31], v[124:127], v[72:75], v[16:31]
	v_exp_f32_e32 v84, v84
	v_exp_f32_e32 v85, v85
	v_exp_f32_e32 v86, v86
	v_exp_f32_e32 v87, v87
	s_waitcnt lgkmcnt(11)
	v_mfma_f32_32x32x16_bf16 v[32:47], v[120:123], v[76:79], v[32:47]
	v_exp_f32_e32 v88, v88
	v_exp_f32_e32 v89, v89
	v_exp_f32_e32 v90, v90
	v_exp_f32_e32 v91, v91
	s_waitcnt lgkmcnt(9)
	v_mfma_f32_32x32x16_bf16 v[16:31], v[120:123], v[148:151], v[16:31]
	v_exp_f32_e32 v92, v92
	v_exp_f32_e32 v93, v93
	v_exp_f32_e32 v94, v94
	v_exp_f32_e32 v95, v95
	s_waitcnt vmcnt(2) lgkmcnt(0)
	s_barrier
	s_andn2_b64 vcc, exec, s[16:17]
	v_add_u32_e32 v0, s40, v201
	s_cbranch_vccnz .LBB0_1608
	s_waitcnt lgkmcnt(0)
	ds_read_b128 v[2:5], v0 offset:49248
	ds_read_b128 v[10:13], v0 offset:49216
	ds_read_b128 v[48:51], v0 offset:49184
	ds_read_b128 v[52:55], v0 offset:49152
	s_waitcnt lgkmcnt(3)
	v_pk_mul_f32 v[44:45], v[44:45], v[2:3]
	s_waitcnt lgkmcnt(2)
	v_pk_mul_f32 v[40:41], v[40:41], v[10:11]
	s_waitcnt lgkmcnt(1)
	v_pk_mul_f32 v[36:37], v[36:37], v[48:49]
	v_pk_mul_f32 v[46:47], v[46:47], v[4:5]
	v_pk_mul_f32 v[42:43], v[42:43], v[12:13]
	v_pk_mul_f32 v[38:39], v[38:39], v[50:51]
	s_waitcnt lgkmcnt(0)
	v_pk_mul_f32 v[34:35], v[34:35], v[54:55]
	v_pk_mul_f32 v[32:33], v[32:33], v[52:53]
	v_pk_mul_f32 v[28:29], v[28:29], v[2:3]
	v_pk_mul_f32 v[24:25], v[24:25], v[10:11]
	v_pk_mul_f32 v[20:21], v[20:21], v[48:49]
	v_pk_mul_f32 v[30:31], v[30:31], v[4:5]
	v_pk_mul_f32 v[26:27], v[26:27], v[12:13]
	v_pk_mul_f32 v[22:23], v[22:23], v[50:51]
	v_pk_mul_f32 v[18:19], v[18:19], v[54:55]
	v_pk_mul_f32 v[16:17], v[16:17], v[52:53]
	s_and_b32 s17, s30, 0x3fffffe0
	v_lshl_add_u32 v2, s17, 2, v194
	ds_read_b32 v48, v2 offset:49408
	s_waitcnt lgkmcnt(0)
.LBB0_1608:
	s_add_i32 s16, s34, 0x2000
	v_bfe_u32 v48, v48, s30, 1
	v_add_u32_e32 v15, s29, v200
	s_cmpk_lg_i32 s34, 0x4000
	s_cselect_b32 s29, s16, 0
	v_cmp_eq_u32_e32 vcc, 1, v48
	s_nop 1
	v_cndmask_b32_e64 v48, v217, -v196, vcc
	v_cndmask_b32_e64 v49, v217, -v196, vcc
	v_mov_b64_e32 v[50:51], v[48:49]
	v_mov_b64_e32 v[52:53], v[48:49]
	v_mov_b64_e32 v[54:55], v[48:49]
	v_mov_b64_e32 v[56:57], v[48:49]
	v_mov_b64_e32 v[58:59], v[48:49]
	v_mov_b64_e32 v[60:61], v[48:49]
	v_mov_b64_e32 v[62:63], v[48:49]
	ds_read_b64_tr_b16 v[2:3], v15 offset:24576
	ds_read_b64_tr_b16 v[4:5], v15 offset:25088
	v_mfma_f32_32x32x16_bf16 v[64:79], v[6:9], v[136:139], v[48:63]
	v_add_f32_e32 v10, v96, v97
	v_add_f32_e32 v10, v98, v10
	v_add_f32_e32 v10, v99, v10
	v_add_f32_e32 v10, v100, v10
	v_add_f32_e32 v10, v101, v10
	v_cvt_pk_bf16_f32 v140, v96, v97
	v_cvt_pk_bf16_f32 v141, v98, v99
	ds_read_b64_tr_b16 v[6:7], v15 offset:28672
	ds_read_b64_tr_b16 v[8:9], v15 offset:29184
	v_mfma_f32_32x32x16_bf16 v[48:63], v[172:175], v[136:139], v[48:63]
	v_add_f32_e32 v10, v102, v10
	v_add_f32_e32 v10, v103, v10
	v_add_f32_e32 v10, v104, v10
	v_add_f32_e32 v96, v105, v10
	v_cvt_pk_bf16_f32 v142, v100, v101
	v_cvt_pk_bf16_f32 v143, v102, v103
	ds_read_b64_tr_b16 v[10:11], v15 offset:25600
	ds_read_b64_tr_b16 v[12:13], v15 offset:26112
	v_mfma_f32_32x32x16_bf16 v[64:79], v[168:171], v[128:131], v[64:79]
	v_add_f32_e32 v96, v106, v96
	v_add_f32_e32 v96, v107, v96
	v_add_f32_e32 v96, v108, v96
	v_add_f32_e32 v100, v109, v96
	v_cvt_pk_bf16_f32 v132, v104, v105
	v_cvt_pk_bf16_f32 v133, v106, v107
	ds_read_b64_tr_b16 v[96:97], v15 offset:29696
	ds_read_b64_tr_b16 v[98:99], v15 offset:30208
	v_mfma_f32_32x32x16_bf16 v[48:63], v[164:167], v[128:131], v[48:63]
	v_add_f32_e32 v100, v110, v100
	v_add_f32_e32 v100, v111, v100
	v_add_f32_e32 v100, v80, v100
	v_add_f32_e32 v104, v81, v100
	v_cvt_pk_bf16_f32 v134, v108, v109
	v_cvt_pk_bf16_f32 v135, v110, v111
	ds_read_b64_tr_b16 v[100:101], v15 offset:26624
	ds_read_b64_tr_b16 v[102:103], v15 offset:27136
	v_mfma_f32_32x32x16_bf16 v[64:79], v[160:163], v[116:119], v[64:79]
	v_add_f32_e32 v104, v82, v104
	v_add_f32_e32 v104, v83, v104
	v_add_f32_e32 v104, v84, v104
	v_add_f32_e32 v108, v85, v104
	v_cvt_pk_bf16_f32 v124, v80, v81
	v_cvt_pk_bf16_f32 v125, v82, v83
	ds_read_b64_tr_b16 v[104:105], v15 offset:30720
	ds_read_b64_tr_b16 v[106:107], v15 offset:31232
	v_mfma_f32_32x32x16_bf16 v[48:63], v[156:159], v[116:119], v[48:63]
	v_add_f32_e32 v80, v86, v108
	v_add_f32_e32 v80, v87, v80
	v_add_f32_e32 v80, v88, v80
	v_add_f32_e32 v80, v89, v80
	v_cvt_pk_bf16_f32 v126, v84, v85
	v_cvt_pk_bf16_f32 v127, v86, v87
	ds_read_b64_tr_b16 v[108:109], v15 offset:27648
	ds_read_b64_tr_b16 v[110:111], v15 offset:28160
	v_mfma_f32_32x32x16_bf16 v[64:79], v[152:155], v[112:115], v[64:79]
	v_add_f32_e32 v80, v90, v80
	v_add_f32_e32 v80, v91, v80
	v_add_f32_e32 v80, v92, v80
	v_add_f32_e32 v80, v93, v80
	v_cvt_pk_bf16_f32 v120, v88, v89
	v_cvt_pk_bf16_f32 v121, v90, v91
	ds_read_b64_tr_b16 v[176:177], v15 offset:31744
	ds_read_b64_tr_b16 v[178:179], v15 offset:32256
	v_mfma_f32_32x32x16_bf16 v[48:63], v[144:147], v[112:115], v[48:63]
	v_add_f32_e32 v15, v94, v80
	v_add_f32_e32 v15, v95, v15
	v_cvt_pk_bf16_f32 v122, v92, v93
	v_cvt_pk_bf16_f32 v123, v94, v95
	v_max_f32_e32 v80, v64, v65
	v_max3_f32 v81, v66, v67, v68
	v_max3_f32 v80, v80, v69, v70
	v_max3_f32 v81, v81, v71, v72
	s_waitcnt lgkmcnt(14)
	v_mfma_f32_32x32x16_bf16 v[32:47], v[140:143], v[2:5], v[32:47]
	v_max3_f32 v80, v80, v73, v74
	v_max3_f32 v81, v81, v75, v76
	v_max3_f32 v80, v80, v77, v78
	v_max3_f32 v81, v81, v79, v80
	v_add_f32_e32 v202, v14, v15
	v_max3_f32 v82, v48, v49, v50
	v_max3_f32 v83, v51, v52, v53
	v_max3_f32 v82, v82, v54, v55
	s_waitcnt lgkmcnt(12)
	v_mfma_f32_32x32x16_bf16 v[16:31], v[140:143], v[6:9], v[16:31]
	v_max3_f32 v83, v83, v56, v57
	v_max3_f32 v82, v82, v58, v59
	v_max3_f32 v83, v83, v60, v61
	v_max3_f32 v82, v82, v62, v63
	v_max3_f32 v14, v82, v83, v81
	v_mov_b32_e32 v15, v14
	s_nop 1
	v_permlane32_swap_b32_e32 v14, v15
	s_add_i32 s16, s34, s44
	s_mov_b32 s17, m0
	s_mov_b32 m0, s16
	s_nop 0
	global_load_lds_dwordx4 v197, s[14:15]
	s_mov_b32 m0, s17
	s_add_u32 s16, s12, 0x8000
	v_max_f32_e32 v14, v14, v15
	s_addc_u32 s17, s13, 0
	s_add_i32 s18, s29, s45
	s_mov_b32 s19, m0
	s_mov_b32 m0, s18
	s_nop 0
	global_load_lds_dwordx4 v198, s[16:17]
	s_mov_b32 m0, s19
	v_cmp_lt_f32_e32 vcc, s47, v14
	s_cmp_lg_u64 vcc, 0
	s_cselect_b64 s[16:17], -1, 0
	s_cbranch_vccnz .LBB0_1616
.LBB0_1609:
	v_exp_f32_e32 v64, v64
	v_exp_f32_e32 v65, v65
	v_exp_f32_e32 v66, v66
	v_exp_f32_e32 v67, v67
	v_exp_f32_e32 v68, v68
	v_exp_f32_e32 v69, v69
	v_exp_f32_e32 v70, v70
	v_exp_f32_e32 v71, v71
	v_add_u32_e32 v2, s29, v199
	ds_read_b128 v[172:175], v2
	ds_read_b128 v[168:171], v2 offset:512
	s_waitcnt lgkmcnt(12)
	v_mfma_f32_32x32x16_bf16 v[32:47], v[132:135], v[10:13], v[32:47]
	v_exp_f32_e32 v72, v72
	v_exp_f32_e32 v73, v73
	v_exp_f32_e32 v74, v74
	v_exp_f32_e32 v75, v75
	ds_read_b128 v[164:167], v2 offset:2048
	ds_read_b128 v[160:163], v2 offset:2560
	s_waitcnt lgkmcnt(12)
	v_mfma_f32_32x32x16_bf16 v[16:31], v[132:135], v[96:99], v[16:31]
	v_exp_f32_e32 v76, v76
	v_exp_f32_e32 v77, v77
	v_exp_f32_e32 v78, v78
	v_exp_f32_e32 v79, v79
	ds_read_b128 v[156:159], v2 offset:4096
	ds_read_b128 v[152:155], v2 offset:4608
	s_waitcnt lgkmcnt(12)
	v_mfma_f32_32x32x16_bf16 v[32:47], v[124:127], v[100:103], v[32:47]
	v_exp_f32_e32 v48, v48
	v_exp_f32_e32 v49, v49
	v_exp_f32_e32 v50, v50
	v_exp_f32_e32 v51, v51
	ds_read_b128 v[148:151], v2 offset:6144
	ds_read_b128 v[144:147], v2 offset:6656
	s_add_i32 s18, s30, 1
	s_and_b32 s18, s18, 0x3fffffe0
	v_lshl_add_u32 v2, s18, 2, v194
	ds_read_b32 v80, v2 offset:49408
	s_waitcnt lgkmcnt(13)
	v_mfma_f32_32x32x16_bf16 v[16:31], v[124:127], v[104:107], v[16:31]
	v_exp_f32_e32 v52, v52
	v_exp_f32_e32 v53, v53
	v_exp_f32_e32 v54, v54
	v_exp_f32_e32 v55, v55
	s_waitcnt lgkmcnt(11)
	v_mfma_f32_32x32x16_bf16 v[32:47], v[120:123], v[108:111], v[32:47]
	v_exp_f32_e32 v56, v56
	v_exp_f32_e32 v57, v57
	v_exp_f32_e32 v58, v58
	v_exp_f32_e32 v59, v59
	s_waitcnt lgkmcnt(9)
	v_mfma_f32_32x32x16_bf16 v[16:31], v[120:123], v[176:179], v[16:31]
	v_exp_f32_e32 v60, v60
	v_exp_f32_e32 v61, v61
	v_exp_f32_e32 v62, v62
	v_exp_f32_e32 v63, v63
	s_waitcnt vmcnt(2) lgkmcnt(0)
	s_barrier
	s_andn2_b64 vcc, exec, s[16:17]
	s_cbranch_vccnz .LBB0_1611
	s_waitcnt lgkmcnt(0)
	ds_read_b128 v[2:5], v0 offset:49248
	ds_read_b128 v[6:9], v0 offset:49216
	ds_read_b128 v[10:13], v0 offset:49184
	ds_read_b128 v[80:83], v0 offset:49152
	s_waitcnt lgkmcnt(3)
	v_pk_mul_f32 v[44:45], v[44:45], v[2:3]
	s_waitcnt lgkmcnt(2)
	v_pk_mul_f32 v[40:41], v[40:41], v[6:7]
	s_waitcnt lgkmcnt(1)
	v_pk_mul_f32 v[36:37], v[36:37], v[10:11]
	v_pk_mul_f32 v[46:47], v[46:47], v[4:5]
	v_pk_mul_f32 v[42:43], v[42:43], v[8:9]
	v_pk_mul_f32 v[38:39], v[38:39], v[12:13]
	s_waitcnt lgkmcnt(0)
	v_pk_mul_f32 v[34:35], v[34:35], v[82:83]
	v_pk_mul_f32 v[32:33], v[32:33], v[80:81]
	v_pk_mul_f32 v[28:29], v[28:29], v[2:3]
	v_pk_mul_f32 v[24:25], v[24:25], v[6:7]
	v_pk_mul_f32 v[20:21], v[20:21], v[10:11]
	v_pk_mul_f32 v[30:31], v[30:31], v[4:5]
	v_pk_mul_f32 v[26:27], v[26:27], v[8:9]
	v_pk_mul_f32 v[22:23], v[22:23], v[12:13]
	v_pk_mul_f32 v[18:19], v[18:19], v[82:83]
	v_pk_mul_f32 v[16:17], v[16:17], v[80:81]
	s_add_i32 s17, s30, 1
	s_and_b32 s17, s17, 0x3fffffe0
	v_lshl_add_u32 v2, s17, 2, v194
	ds_read_b32 v80, v2 offset:49408
	s_waitcnt lgkmcnt(0)
